# prep1_qk and prep0_q per-head rmsnorm wave reductions batched (5-7 independent ds_bpermute chains interleaved instead of serialized)
# speedup vs baseline: 1.0046x; 1.0046x over previous
; DEVI bf16_t f2bf(float f) { return (bf16_t)(pk2(f, 0.f) & 0xffffu); }
; DEVI void prep0_q(int sw, const P& p, int item) {
;     ...
;   for (int h = 0; h < 8; ++h) {
;     float ss = wave_sum(a[h] * a[h] + b[h] * b[h] + c[h] * c[h]);
;     float rs = rsqrtf(ss * (1.f / 192.f) + EPS);
;     float x = a[h] * rs * g0, y = b[h] * rs * g1, z = c[h] * rs * g2;
;     if (pp >= CTX) z = rope64(z, lane, pp - CTX);
;     qb[h * 192 + lane] = f2bf(x * sc); qb[h * 192 + 64 + lane] = f2bf(y * sc); qb[h * 192 + 128 + lane] = f2bf(z * sc);
.LBB0_471:
	v_mul_f32_e32 v5, v38, v5
	v_mul_f32_e32 v5, v6, v5
	v_mul_f32_e32 v35, v38, v35
	v_mul_f32_e32 v5, 0x3dd53b94, v5
	v_mul_f32_e32 v35, v7, v35
	v_cvt_pk_bf16_f32 v5, v5, s0
	global_store_short v[0:1], v5, off
	v_mul_f32_e32 v5, 0x3dd53b94, v35
	v_cvt_pk_bf16_f32 v5, v5, s0
	global_store_short v[0:1], v5, off offset:128
	v_mul_f32_e32 v5, 0x3dd53b94, v37
	v_cvt_pk_bf16_f32 v5, v5, s0
	global_store_short v[0:1], v5, off offset:256
	v_lshlrev_b32_e32 v2, 16, v2
	v_lshlrev_b32_e32 v3, 16, v3
	v_lshlrev_b32_e32 v36, 16, v36
	v_lshlrev_b32_e32 v32, 16, v32
	v_lshlrev_b32_e32 v34, 16, v34
	v_lshlrev_b32_e32 v33, 16, v33
	v_lshlrev_b32_e32 v29, 16, v29
	v_lshlrev_b32_e32 v31, 16, v31
	v_lshlrev_b32_e32 v30, 16, v30
	v_lshlrev_b32_e32 v26, 16, v26
	v_lshlrev_b32_e32 v28, 16, v28
	v_lshlrev_b32_e32 v27, 16, v27
	v_lshlrev_b32_e32 v23, 16, v23
	v_lshlrev_b32_e32 v25, 16, v25
	v_lshlrev_b32_e32 v24, 16, v24
	v_lshlrev_b32_e32 v20, 16, v20
	v_lshlrev_b32_e32 v22, 16, v22
	v_lshlrev_b32_e32 v21, 16, v21
	v_lshlrev_b32_e32 v17, 16, v17
	v_lshlrev_b32_e32 v19, 16, v19
	v_lshlrev_b32_e32 v18, 16, v18
	v_mul_f32_e32 v220, v2, v2
	v_mul_f32_e32 v221, v36, v36
	v_fma_f32 v220, v3, v3, v220
	v_add_f32_e32 v220, v221, v220
	v_mul_f32_e32 v223, v32, v32
	v_mul_f32_e32 v224, v33, v33
	v_fma_f32 v223, v34, v34, v223
	v_add_f32_e32 v223, v224, v223
	v_mul_f32_e32 v226, v29, v29
	v_mul_f32_e32 v227, v30, v30
	v_fma_f32 v226, v31, v31, v226
	v_add_f32_e32 v226, v227, v226
	v_mul_f32_e32 v229, v26, v26
	v_mul_f32_e32 v230, v27, v27
	v_fma_f32 v229, v28, v28, v229
	v_add_f32_e32 v229, v230, v229
	v_mul_f32_e32 v232, v23, v23
	v_mul_f32_e32 v233, v24, v24
	v_fma_f32 v232, v25, v25, v232
	v_add_f32_e32 v232, v233, v232
	v_mul_f32_e32 v235, v20, v20
	v_mul_f32_e32 v236, v21, v21
	v_fma_f32 v235, v22, v22, v235
	v_add_f32_e32 v235, v236, v235
	v_mul_f32_e32 v238, v17, v17
	v_mul_f32_e32 v239, v18, v18
	v_fma_f32 v238, v19, v19, v238
	v_add_f32_e32 v238, v239, v238
	ds_bpermute_b32 v221, v14, v220
	ds_bpermute_b32 v224, v14, v223
	ds_bpermute_b32 v227, v14, v226
	ds_bpermute_b32 v230, v14, v229
	ds_bpermute_b32 v233, v14, v232
	ds_bpermute_b32 v236, v14, v235
	ds_bpermute_b32 v239, v14, v238
	s_waitcnt lgkmcnt(0)
	v_add_f32_e32 v220, v220, v221
	v_add_f32_e32 v223, v223, v224
	v_add_f32_e32 v226, v226, v227
	v_add_f32_e32 v229, v229, v230
	v_add_f32_e32 v232, v232, v233
	v_add_f32_e32 v235, v235, v236
	v_add_f32_e32 v238, v238, v239
	ds_bpermute_b32 v221, v9, v220
	ds_bpermute_b32 v224, v9, v223
	ds_bpermute_b32 v227, v9, v226
	ds_bpermute_b32 v230, v9, v229
	ds_bpermute_b32 v233, v9, v232
	ds_bpermute_b32 v236, v9, v235
	ds_bpermute_b32 v239, v9, v238
	s_waitcnt lgkmcnt(0)
	v_add_f32_e32 v220, v220, v221
	v_add_f32_e32 v223, v223, v224
	v_add_f32_e32 v226, v226, v227
	v_add_f32_e32 v229, v229, v230
	v_add_f32_e32 v232, v232, v233
	v_add_f32_e32 v235, v235, v236
	v_add_f32_e32 v238, v238, v239
	ds_bpermute_b32 v221, v15, v220
	ds_bpermute_b32 v224, v15, v223
	ds_bpermute_b32 v227, v15, v226
	ds_bpermute_b32 v230, v15, v229
	ds_bpermute_b32 v233, v15, v232
	ds_bpermute_b32 v236, v15, v235
	ds_bpermute_b32 v239, v15, v238
	s_waitcnt lgkmcnt(0)
	v_add_f32_e32 v220, v220, v221
	v_add_f32_e32 v223, v223, v224
	v_add_f32_e32 v226, v226, v227
	v_add_f32_e32 v229, v229, v230
	v_add_f32_e32 v232, v232, v233
	v_add_f32_e32 v235, v235, v236
	v_add_f32_e32 v238, v238, v239
	ds_bpermute_b32 v221, v16, v220
	ds_bpermute_b32 v224, v16, v223
	ds_bpermute_b32 v227, v16, v226
	ds_bpermute_b32 v230, v16, v229
	ds_bpermute_b32 v233, v16, v232
	ds_bpermute_b32 v236, v16, v235
	ds_bpermute_b32 v239, v16, v238
	s_waitcnt lgkmcnt(0)
	v_add_f32_e32 v220, v220, v221
	v_add_f32_e32 v223, v223, v224
	v_add_f32_e32 v226, v226, v227
	v_add_f32_e32 v229, v229, v230
	v_add_f32_e32 v232, v232, v233
	v_add_f32_e32 v235, v235, v236
	v_add_f32_e32 v238, v238, v239
	ds_bpermute_b32 v221, v13, v220
	ds_bpermute_b32 v224, v13, v223
	ds_bpermute_b32 v227, v13, v226
	ds_bpermute_b32 v230, v13, v229
	ds_bpermute_b32 v233, v13, v232
	ds_bpermute_b32 v236, v13, v235
	ds_bpermute_b32 v239, v13, v238
	s_waitcnt lgkmcnt(0)
	v_add_f32_e32 v220, v220, v221
	v_add_f32_e32 v223, v223, v224
	v_add_f32_e32 v226, v226, v227
	v_add_f32_e32 v229, v229, v230
	v_add_f32_e32 v232, v232, v233
	v_add_f32_e32 v235, v235, v236
	v_add_f32_e32 v238, v238, v239
	ds_bpermute_b32 v221, v12, v220
	ds_bpermute_b32 v224, v12, v223
	ds_bpermute_b32 v227, v12, v226
	ds_bpermute_b32 v230, v12, v229
	ds_bpermute_b32 v233, v12, v232
	ds_bpermute_b32 v236, v12, v235
	ds_bpermute_b32 v239, v12, v238
	s_waitcnt lgkmcnt(0)
; DEVI float rope64(float val, int lane, int t) {
;   int i = lane & 15, hf = (lane >> 4) & 1, axis = lane >> 5;
;   float pos = (float)(axis ? (t & 63) : (t >> 6));
;   float invf = exp2f(-(float)(2 * i) * (13.287712379549449f / 32.f));
;   float ang = pos * invf;
;   float cs = __cosf(ang), sn = __sinf(ang);
;   float partner = __shfl_xor(val, 16);
;   return hf ? (val * cs + partner * sn) : (val * cs - partner * sn);
; DEVI void prep0_q(int sw, const P& p, int item) {
;     ...
;     float ss = wave_sum(a[h] * a[h] + b[h] * b[h] + c[h] * c[h]);
;     float rs = rsqrtf(ss * (1.f / 192.f) + EPS);
;     float x = a[h] * rs * g0, y = b[h] * rs * g1, z = c[h] * rs * g2;
;     if (pp >= CTX) z = rope64(z, lane, pp - CTX);
	v_add_f32_e32 v220, v220, v221
	v_add_f32_e32 v223, v223, v224
	v_add_f32_e32 v226, v226, v227
	v_add_f32_e32 v229, v229, v230
	v_add_f32_e32 v232, v232, v233
	v_add_f32_e32 v235, v235, v236
	v_add_f32_e32 v238, v238, v239
	v_fmamk_f32 v220, v220, 0x3baaaaab, v48
	v_fmamk_f32 v223, v223, 0x3baaaaab, v48
	v_fmamk_f32 v226, v226, 0x3baaaaab, v48
	v_fmamk_f32 v229, v229, 0x3baaaaab, v48
	v_fmamk_f32 v232, v232, 0x3baaaaab, v48
	v_fmamk_f32 v235, v235, 0x3baaaaab, v48
	v_fmamk_f32 v238, v238, 0x3baaaaab, v48
	v_cmp_gt_f32_e32 vcc, s95, v220
	v_mul_f32_e32 v221, 0x4b800000, v220
	s_nop 0
	v_cndmask_b32_e32 v220, v220, v221, vcc
	v_rsq_f32_e32 v220, v220
	s_nop 0
	v_mul_f32_e32 v221, 0x45800000, v220
	v_cndmask_b32_e32 v222, v220, v221, vcc
	v_cmp_gt_f32_e32 vcc, s95, v223
	v_mul_f32_e32 v224, 0x4b800000, v223
	s_nop 0
	v_cndmask_b32_e32 v223, v223, v224, vcc
	v_rsq_f32_e32 v223, v223
	s_nop 0
	v_mul_f32_e32 v224, 0x45800000, v223
	v_cndmask_b32_e32 v225, v223, v224, vcc
	v_cmp_gt_f32_e32 vcc, s95, v226
	v_mul_f32_e32 v227, 0x4b800000, v226
	s_nop 0
	v_cndmask_b32_e32 v226, v226, v227, vcc
	v_rsq_f32_e32 v226, v226
	s_nop 0
	v_mul_f32_e32 v227, 0x45800000, v226
	v_cndmask_b32_e32 v228, v226, v227, vcc
	v_cmp_gt_f32_e32 vcc, s95, v229
	v_mul_f32_e32 v230, 0x4b800000, v229
	s_nop 0
	v_cndmask_b32_e32 v229, v229, v230, vcc
	v_rsq_f32_e32 v229, v229
	s_nop 0
	v_mul_f32_e32 v230, 0x45800000, v229
	v_cndmask_b32_e32 v231, v229, v230, vcc
	v_cmp_gt_f32_e32 vcc, s95, v232
	v_mul_f32_e32 v233, 0x4b800000, v232
	s_nop 0
	v_cndmask_b32_e32 v232, v232, v233, vcc
	v_rsq_f32_e32 v232, v232
	s_nop 0
	v_mul_f32_e32 v233, 0x45800000, v232
	v_cndmask_b32_e32 v234, v232, v233, vcc
	v_cmp_gt_f32_e32 vcc, s95, v235
	v_mul_f32_e32 v236, 0x4b800000, v235
	s_nop 0
	v_cndmask_b32_e32 v235, v235, v236, vcc
	v_rsq_f32_e32 v235, v235
	s_nop 0
	v_mul_f32_e32 v236, 0x45800000, v235
	v_cndmask_b32_e32 v237, v235, v236, vcc
	v_cmp_gt_f32_e32 vcc, s95, v238
	v_mul_f32_e32 v239, 0x4b800000, v238
	s_nop 0
	v_cndmask_b32_e32 v238, v238, v239, vcc
	v_rsq_f32_e32 v238, v238
	s_nop 0
	v_mul_f32_e32 v239, 0x45800000, v238
	v_cndmask_b32_e32 v240, v238, v239, vcc
	v_mul_f32_e32 v36, v222, v36
	v_mul_f32_e32 v36, v8, v36
	v_mul_f32_e32 v33, v225, v33
	v_mul_f32_e32 v33, v8, v33
	v_mul_f32_e32 v30, v228, v30
	v_mul_f32_e32 v30, v8, v30
	v_mul_f32_e32 v27, v231, v27
	v_mul_f32_e32 v27, v8, v27
	v_mul_f32_e32 v24, v234, v24
	v_mul_f32_e32 v24, v8, v24
	v_mul_f32_e32 v21, v237, v21
	v_mul_f32_e32 v21, v8, v21
	v_mul_f32_e32 v18, v240, v18
	v_mul_f32_e32 v18, v8, v18
	s_andn2_b64 vcc, exec, s[4:5]
	s_cbranch_vccnz .Lmy_q0_norope
	ds_bpermute_b32 v221, v9, v36
	ds_bpermute_b32 v224, v9, v33
	ds_bpermute_b32 v227, v9, v30
	ds_bpermute_b32 v230, v9, v27
	ds_bpermute_b32 v233, v9, v24
	ds_bpermute_b32 v236, v9, v21
	ds_bpermute_b32 v239, v9, v18
	s_waitcnt lgkmcnt(0)
	v_mul_f32_e32 v221, v11, v221
	v_cndmask_b32_e64 v221, v221, -v221, s[0:1]
	v_fmac_f32_e32 v221, v10, v36
	v_mov_b32_e32 v36, v221
	v_mul_f32_e32 v224, v11, v224
	v_cndmask_b32_e64 v224, v224, -v224, s[0:1]
	v_fmac_f32_e32 v224, v10, v33
	v_mov_b32_e32 v33, v224
	v_mul_f32_e32 v227, v11, v227
	v_cndmask_b32_e64 v227, v227, -v227, s[0:1]
	v_fmac_f32_e32 v227, v10, v30
	v_mov_b32_e32 v30, v227
	v_mul_f32_e32 v230, v11, v230
	v_cndmask_b32_e64 v230, v230, -v230, s[0:1]
	v_fmac_f32_e32 v230, v10, v27
	v_mov_b32_e32 v27, v230
	v_mul_f32_e32 v233, v11, v233
	v_cndmask_b32_e64 v233, v233, -v233, s[0:1]
	v_fmac_f32_e32 v233, v10, v24
	v_mov_b32_e32 v24, v233
	v_mul_f32_e32 v236, v11, v236
	v_cndmask_b32_e64 v236, v236, -v236, s[0:1]
	v_fmac_f32_e32 v236, v10, v21
	v_mov_b32_e32 v21, v236
	v_mul_f32_e32 v239, v11, v239
	v_cndmask_b32_e64 v239, v239, -v239, s[0:1]
	v_fmac_f32_e32 v239, v10, v18
	v_mov_b32_e32 v18, v239
; DEVI bf16_t f2bf(float f) { return (bf16_t)(pk2(f, 0.f) & 0xffffu); }
; DEVI void prep0_q(int sw, const P& p, int item) {
;     ...
;     float x = a[h] * rs * g0, y = b[h] * rs * g1, z = c[h] * rs * g2;
;     if (pp >= CTX) z = rope64(z, lane, pp - CTX);
;     qb[h * 192 + lane] = f2bf(x * sc); qb[h * 192 + 64 + lane] = f2bf(y * sc); qb[h * 192 + 128 + lane] = f2bf(z * sc);
.Lmy_q0_norope:
	v_mul_f32_e32 v2, v222, v2
	v_mul_f32_e32 v2, v6, v2
	v_mul_f32_e32 v2, 0x3dd53b94, v2
	v_cvt_pk_bf16_f32 v2, v2, s0
	global_store_short v[0:1], v2, off offset:384
	v_mul_f32_e32 v3, v222, v3
	v_mul_f32_e32 v3, v7, v3
	v_mul_f32_e32 v3, 0x3dd53b94, v3
	v_cvt_pk_bf16_f32 v3, v3, s0
	global_store_short v[0:1], v3, off offset:512
	v_mul_f32_e32 v36, 0x3dd53b94, v36
	v_cvt_pk_bf16_f32 v36, v36, s0
	global_store_short v[0:1], v36, off offset:640
	v_mul_f32_e32 v32, v225, v32
	v_mul_f32_e32 v32, v6, v32
	v_mul_f32_e32 v32, 0x3dd53b94, v32
	v_cvt_pk_bf16_f32 v32, v32, s0
	global_store_short v[0:1], v32, off offset:768
	v_mul_f32_e32 v34, v225, v34
	v_mul_f32_e32 v34, v7, v34
	v_mul_f32_e32 v34, 0x3dd53b94, v34
	v_cvt_pk_bf16_f32 v34, v34, s0
	global_store_short v[0:1], v34, off offset:896
	v_mul_f32_e32 v33, 0x3dd53b94, v33
	v_cvt_pk_bf16_f32 v33, v33, s0
	global_store_short v[0:1], v33, off offset:1024
	v_mul_f32_e32 v29, v228, v29
	v_mul_f32_e32 v29, v6, v29
	v_mul_f32_e32 v29, 0x3dd53b94, v29
	v_cvt_pk_bf16_f32 v29, v29, s0
	global_store_short v[0:1], v29, off offset:1152
	v_mul_f32_e32 v31, v228, v31
	v_mul_f32_e32 v31, v7, v31
	v_mul_f32_e32 v31, 0x3dd53b94, v31
	v_cvt_pk_bf16_f32 v31, v31, s0
	global_store_short v[0:1], v31, off offset:1280
	v_mul_f32_e32 v30, 0x3dd53b94, v30
	v_cvt_pk_bf16_f32 v30, v30, s0
	global_store_short v[0:1], v30, off offset:1408
	v_mul_f32_e32 v26, v231, v26
	v_mul_f32_e32 v26, v6, v26
	v_mul_f32_e32 v26, 0x3dd53b94, v26
	v_cvt_pk_bf16_f32 v26, v26, s0
	global_store_short v[0:1], v26, off offset:1536
	v_mul_f32_e32 v28, v231, v28
	v_mul_f32_e32 v28, v7, v28
	v_mul_f32_e32 v28, 0x3dd53b94, v28
	v_cvt_pk_bf16_f32 v28, v28, s0
	global_store_short v[0:1], v28, off offset:1664
	v_mul_f32_e32 v27, 0x3dd53b94, v27
	v_cvt_pk_bf16_f32 v27, v27, s0
	global_store_short v[0:1], v27, off offset:1792
	v_mul_f32_e32 v23, v234, v23
	v_mul_f32_e32 v23, v6, v23
	v_mul_f32_e32 v23, 0x3dd53b94, v23
	v_cvt_pk_bf16_f32 v23, v23, s0
	global_store_short v[0:1], v23, off offset:1920
	v_mul_f32_e32 v25, v234, v25
	v_mul_f32_e32 v25, v7, v25
	v_mul_f32_e32 v25, 0x3dd53b94, v25
	v_cvt_pk_bf16_f32 v25, v25, s0
	global_store_short v[0:1], v25, off offset:2048
	v_mul_f32_e32 v24, 0x3dd53b94, v24
	v_cvt_pk_bf16_f32 v24, v24, s0
	global_store_short v[0:1], v24, off offset:2176
	v_mul_f32_e32 v20, v237, v20
	v_mul_f32_e32 v20, v6, v20
	v_mul_f32_e32 v20, 0x3dd53b94, v20
	v_cvt_pk_bf16_f32 v20, v20, s0
	global_store_short v[0:1], v20, off offset:2304
	v_mul_f32_e32 v22, v237, v22
	v_mul_f32_e32 v22, v7, v22
	v_mul_f32_e32 v22, 0x3dd53b94, v22
	v_cvt_pk_bf16_f32 v22, v22, s0
	global_store_short v[0:1], v22, off offset:2432
	v_mul_f32_e32 v21, 0x3dd53b94, v21
	v_cvt_pk_bf16_f32 v21, v21, s0
	global_store_short v[0:1], v21, off offset:2560
	v_mul_f32_e32 v17, v240, v17
	v_mul_f32_e32 v17, v6, v17
	v_mul_f32_e32 v17, 0x3dd53b94, v17
	v_cvt_pk_bf16_f32 v17, v17, s0
	global_store_short v[0:1], v17, off offset:2688
	v_mul_f32_e32 v19, v240, v19
	v_mul_f32_e32 v19, v7, v19
	v_mul_f32_e32 v19, 0x3dd53b94, v19
	v_cvt_pk_bf16_f32 v19, v19, s0
	global_store_short v[0:1], v19, off offset:2816
	v_mul_f32_e32 v18, 0x3dd53b94, v18
	v_cvt_pk_bf16_f32 v18, v18, s0
	global_store_short v[0:1], v18, off offset:2944
	s_not_b64 s[2:3], s[4:5]
	s_mov_b64 s[0:1], 0

; DEVI bf16_t f2bf(float f) { return (bf16_t)(pk2(f, 0.f) & 0xffffu); }
; DEVI void prep1_qk(int sw, const P& p, int item) {
;     ...
;   for (int hm = 0; hm < 16; ++hm) {
;     float ss = wave_sum(a[hm] * a[hm]);
;     float rs = rsqrtf(ss * (1.f / 64.f) + EPS);
;     float x = a[hm] * rs * ((hm & 1) ? g1 : g0);
;     if (pp >= CTX) x = rope64(x, lane, pp - CTX);
;     if (which == 0) x *= 0.125f * LOG2E;
;     q[hm * 64 + lane] = f2bf(x);
.LBB0_1382:
	v_readlane_b32 s0, v219, 32
	v_readlane_b32 s1, v219, 33
	v_mul_f32_e32 v29, 0x3e38aa3b, v2
	s_nop 1
	v_cndmask_b32_e64 v2, v2, v29, s[0:1]
	v_cvt_pk_bf16_f32 v2, v2, s0
	global_store_short v[0:1], v2, off
	s_waitcnt vmcnt(1)
	v_lshlrev_b32_e32 v28, 16, v28
	v_lshlrev_b32_e32 v27, 16, v27
	v_lshlrev_b32_e32 v26, 16, v26
	v_lshlrev_b32_e32 v25, 16, v25
	v_lshlrev_b32_e32 v24, 16, v24
	v_mul_f32_e32 v150, v28, v28
	v_mul_f32_e32 v152, v27, v27
	v_mul_f32_e32 v154, v26, v26
	v_mul_f32_e32 v156, v25, v25
	v_mul_f32_e32 v158, v24, v24
	ds_bpermute_b32 v151, v9, v150
	ds_bpermute_b32 v153, v9, v152
	ds_bpermute_b32 v155, v9, v154
	ds_bpermute_b32 v157, v9, v156
	ds_bpermute_b32 v159, v9, v158
	s_waitcnt lgkmcnt(0)
	v_fmac_f32_e32 v151, v28, v28
	v_fmac_f32_e32 v153, v27, v27
	v_fmac_f32_e32 v155, v26, v26
	v_fmac_f32_e32 v157, v25, v25
	v_fmac_f32_e32 v159, v24, v24
	ds_bpermute_b32 v150, v8, v151
	ds_bpermute_b32 v152, v8, v153
	ds_bpermute_b32 v154, v8, v155
	ds_bpermute_b32 v156, v8, v157
	ds_bpermute_b32 v158, v8, v159
	s_waitcnt lgkmcnt(0)
	v_add_f32_e32 v151, v151, v150
	v_add_f32_e32 v153, v153, v152
	v_add_f32_e32 v155, v155, v154
	v_add_f32_e32 v157, v157, v156
	v_add_f32_e32 v159, v159, v158
	ds_bpermute_b32 v150, v10, v151
	ds_bpermute_b32 v152, v10, v153
	ds_bpermute_b32 v154, v10, v155
	ds_bpermute_b32 v156, v10, v157
	ds_bpermute_b32 v158, v10, v159
	s_waitcnt lgkmcnt(0)
	v_add_f32_e32 v151, v151, v150
	v_add_f32_e32 v153, v153, v152
	v_add_f32_e32 v155, v155, v154
	v_add_f32_e32 v157, v157, v156
	v_add_f32_e32 v159, v159, v158
	ds_bpermute_b32 v150, v11, v151
	ds_bpermute_b32 v152, v11, v153
	ds_bpermute_b32 v154, v11, v155
	ds_bpermute_b32 v156, v11, v157
	ds_bpermute_b32 v158, v11, v159
	s_waitcnt lgkmcnt(0)
	v_add_f32_e32 v151, v151, v150
	v_add_f32_e32 v153, v153, v152
	v_add_f32_e32 v155, v155, v154
	v_add_f32_e32 v157, v157, v156
	v_add_f32_e32 v159, v159, v158
	ds_bpermute_b32 v150, v12, v151
	ds_bpermute_b32 v152, v12, v153
	ds_bpermute_b32 v154, v12, v155
	ds_bpermute_b32 v156, v12, v157
	ds_bpermute_b32 v158, v12, v159
	s_waitcnt lgkmcnt(0)
	v_add_f32_e32 v151, v151, v150
	v_add_f32_e32 v153, v153, v152
	v_add_f32_e32 v155, v155, v154
	v_add_f32_e32 v157, v157, v156
	v_add_f32_e32 v159, v159, v158
	ds_bpermute_b32 v150, v13, v151
	ds_bpermute_b32 v152, v13, v153
	ds_bpermute_b32 v154, v13, v155
	ds_bpermute_b32 v156, v13, v157
	ds_bpermute_b32 v158, v13, v159
	s_waitcnt lgkmcnt(0)
	v_add_f32_e32 v151, v151, v150
	v_add_f32_e32 v153, v153, v152
	v_add_f32_e32 v155, v155, v154
	v_add_f32_e32 v157, v157, v156
	v_add_f32_e32 v159, v159, v158
	v_fmamk_f32 v151, v151, 0x3c800000, v36
	v_fmamk_f32 v153, v153, 0x3c800000, v36
	v_fmamk_f32 v155, v155, 0x3c800000, v36
	v_fmamk_f32 v157, v157, 0x3c800000, v36
	v_fmamk_f32 v159, v159, 0x3c800000, v36
	v_cmp_gt_f32_e32 vcc, s58, v151
	v_mul_f32_e32 v150, 0x4b800000, v151
	s_nop 0
	v_cndmask_b32_e32 v151, v151, v150, vcc
	v_rsq_f32_e32 v151, v151
	s_nop 0
	v_mul_f32_e32 v150, 0x45800000, v151
	v_cndmask_b32_e32 v151, v151, v150, vcc
	v_cmp_gt_f32_e32 vcc, s58, v153
	v_mul_f32_e32 v152, 0x4b800000, v153
	s_nop 0
	v_cndmask_b32_e32 v153, v153, v152, vcc
	v_rsq_f32_e32 v153, v153
	s_nop 0
	v_mul_f32_e32 v152, 0x45800000, v153
	v_cndmask_b32_e32 v153, v153, v152, vcc
	v_cmp_gt_f32_e32 vcc, s58, v155
	v_mul_f32_e32 v154, 0x4b800000, v155
	s_nop 0
	v_cndmask_b32_e32 v155, v155, v154, vcc
	v_rsq_f32_e32 v155, v155
	s_nop 0
	v_mul_f32_e32 v154, 0x45800000, v155
	v_cndmask_b32_e32 v155, v155, v154, vcc
	v_cmp_gt_f32_e32 vcc, s58, v157
	v_mul_f32_e32 v156, 0x4b800000, v157
	s_nop 0
	v_cndmask_b32_e32 v157, v157, v156, vcc
	v_rsq_f32_e32 v157, v157
	s_nop 0
	v_mul_f32_e32 v156, 0x45800000, v157
	v_cndmask_b32_e32 v157, v157, v156, vcc
	v_cmp_gt_f32_e32 vcc, s58, v159
	v_mul_f32_e32 v158, 0x4b800000, v159
	s_nop 0
	v_cndmask_b32_e32 v159, v159, v158, vcc
	v_rsq_f32_e32 v159, v159
	s_nop 0
	v_mul_f32_e32 v158, 0x45800000, v159
	v_cndmask_b32_e32 v159, v159, v158, vcc
	v_mul_f32_e32 v151, v151, v28
	v_mul_f32_e32 v151, v3, v151
	v_mul_f32_e32 v153, v153, v27
	v_mul_f32_e32 v153, v6, v153
	v_mul_f32_e32 v155, v155, v26
	v_mul_f32_e32 v155, v3, v155
	v_mul_f32_e32 v157, v157, v25
	v_mul_f32_e32 v157, v6, v157
	v_mul_f32_e32 v159, v159, v24
	v_mul_f32_e32 v159, v3, v159
	s_andn2_b64 vcc, exec, s[12:13]
	s_cbranch_vccnz .Lmy_norope_1
	ds_bpermute_b32 v150, v8, v151
	ds_bpermute_b32 v152, v8, v153
	ds_bpermute_b32 v154, v8, v155
	ds_bpermute_b32 v156, v8, v157
	ds_bpermute_b32 v158, v8, v159
	s_waitcnt lgkmcnt(0)
	v_mul_f32_e32 v150, v16, v150
	v_cndmask_b32_e64 v150, v150, -v150, s[2:3]
	v_fmac_f32_e32 v150, v15, v151
	v_mov_b32_e32 v151, v150
	v_mul_f32_e32 v152, v16, v152
	v_cndmask_b32_e64 v152, v152, -v152, s[2:3]
	v_fmac_f32_e32 v152, v15, v153
	v_mov_b32_e32 v153, v152
	v_mul_f32_e32 v154, v16, v154
	v_cndmask_b32_e64 v154, v154, -v154, s[2:3]
	v_fmac_f32_e32 v154, v15, v155
	v_mov_b32_e32 v155, v154
	v_mul_f32_e32 v156, v16, v156
	v_cndmask_b32_e64 v156, v156, -v156, s[2:3]
	v_fmac_f32_e32 v156, v15, v157
	v_mov_b32_e32 v157, v156
	v_mul_f32_e32 v158, v16, v158
	v_cndmask_b32_e64 v158, v158, -v158, s[2:3]
	v_fmac_f32_e32 v158, v15, v159
	v_mov_b32_e32 v159, v158
; DEVI bf16_t f2bf(float f) { return (bf16_t)(pk2(f, 0.f) & 0xffffu); }
; DEVI void prep1_qk(int sw, const P& p, int item) {
;     ...
;   for (int hm = 0; hm < 16; ++hm) {
;     float ss = wave_sum(a[hm] * a[hm]);
;     float rs = rsqrtf(ss * (1.f / 64.f) + EPS);
;     float x = a[hm] * rs * ((hm & 1) ? g1 : g0);
;     if (pp >= CTX) x = rope64(x, lane, pp - CTX);
;     if (which == 0) x *= 0.125f * LOG2E;
;     q[hm * 64 + lane] = f2bf(x);
.Lmy_norope_1:
	v_mul_f32_e32 v150, 0x3e38aa3b, v151
	v_cndmask_b32_e64 v151, v151, v150, s[0:1]
	v_cvt_pk_bf16_f32 v151, v151, s0
	global_store_short v[0:1], v151, off offset:128
	v_mul_f32_e32 v152, 0x3e38aa3b, v153
	v_cndmask_b32_e64 v153, v153, v152, s[0:1]
	v_cvt_pk_bf16_f32 v153, v153, s0
	global_store_short v[0:1], v153, off offset:256
	v_mul_f32_e32 v154, 0x3e38aa3b, v155
	v_cndmask_b32_e64 v155, v155, v154, s[0:1]
	v_cvt_pk_bf16_f32 v155, v155, s0
	global_store_short v[0:1], v155, off offset:384
	v_mul_f32_e32 v156, 0x3e38aa3b, v157
	v_cndmask_b32_e64 v157, v157, v156, s[0:1]
	v_cvt_pk_bf16_f32 v157, v157, s0
	global_store_short v[0:1], v157, off offset:512
	v_mul_f32_e32 v158, 0x3e38aa3b, v159
	v_cndmask_b32_e64 v159, v159, v158, s[0:1]
	v_cvt_pk_bf16_f32 v159, v159, s0
	global_store_short v[0:1], v159, off offset:640
	v_lshlrev_b32_e32 v23, 16, v23
	v_lshlrev_b32_e32 v22, 16, v22
	v_lshlrev_b32_e32 v21, 16, v21
	v_lshlrev_b32_e32 v20, 16, v20
	v_lshlrev_b32_e32 v19, 16, v19
	v_mul_f32_e32 v150, v23, v23
	v_mul_f32_e32 v152, v22, v22
	v_mul_f32_e32 v154, v21, v21
	v_mul_f32_e32 v156, v20, v20
	v_mul_f32_e32 v158, v19, v19
	ds_bpermute_b32 v151, v9, v150
	ds_bpermute_b32 v153, v9, v152
	ds_bpermute_b32 v155, v9, v154
	ds_bpermute_b32 v157, v9, v156
	ds_bpermute_b32 v159, v9, v158
	s_waitcnt lgkmcnt(0)
	v_fmac_f32_e32 v151, v23, v23
	v_fmac_f32_e32 v153, v22, v22
	v_fmac_f32_e32 v155, v21, v21
	v_fmac_f32_e32 v157, v20, v20
	v_fmac_f32_e32 v159, v19, v19
	ds_bpermute_b32 v150, v8, v151
	ds_bpermute_b32 v152, v8, v153
	ds_bpermute_b32 v154, v8, v155
	ds_bpermute_b32 v156, v8, v157
	ds_bpermute_b32 v158, v8, v159
	s_waitcnt lgkmcnt(0)
	v_add_f32_e32 v151, v151, v150
	v_add_f32_e32 v153, v153, v152
	v_add_f32_e32 v155, v155, v154
	v_add_f32_e32 v157, v157, v156
	v_add_f32_e32 v159, v159, v158
	ds_bpermute_b32 v150, v10, v151
	ds_bpermute_b32 v152, v10, v153
	ds_bpermute_b32 v154, v10, v155
	ds_bpermute_b32 v156, v10, v157
	ds_bpermute_b32 v158, v10, v159
	s_waitcnt lgkmcnt(0)
	v_add_f32_e32 v151, v151, v150
	v_add_f32_e32 v153, v153, v152
	v_add_f32_e32 v155, v155, v154
	v_add_f32_e32 v157, v157, v156
	v_add_f32_e32 v159, v159, v158
	ds_bpermute_b32 v150, v11, v151
	ds_bpermute_b32 v152, v11, v153
	ds_bpermute_b32 v154, v11, v155
	ds_bpermute_b32 v156, v11, v157
	ds_bpermute_b32 v158, v11, v159
	s_waitcnt lgkmcnt(0)
	v_add_f32_e32 v151, v151, v150
	v_add_f32_e32 v153, v153, v152
	v_add_f32_e32 v155, v155, v154
	v_add_f32_e32 v157, v157, v156
	v_add_f32_e32 v159, v159, v158
	ds_bpermute_b32 v150, v12, v151
	ds_bpermute_b32 v152, v12, v153
	ds_bpermute_b32 v154, v12, v155
	ds_bpermute_b32 v156, v12, v157
	ds_bpermute_b32 v158, v12, v159
	s_waitcnt lgkmcnt(0)
	v_add_f32_e32 v151, v151, v150
	v_add_f32_e32 v153, v153, v152
	v_add_f32_e32 v155, v155, v154
	v_add_f32_e32 v157, v157, v156
	v_add_f32_e32 v159, v159, v158
	ds_bpermute_b32 v150, v13, v151
	ds_bpermute_b32 v152, v13, v153
	ds_bpermute_b32 v154, v13, v155
	ds_bpermute_b32 v156, v13, v157
	ds_bpermute_b32 v158, v13, v159
	s_waitcnt lgkmcnt(0)
	v_add_f32_e32 v151, v151, v150
	v_add_f32_e32 v153, v153, v152
	v_add_f32_e32 v155, v155, v154
	v_add_f32_e32 v157, v157, v156
	v_add_f32_e32 v159, v159, v158
	v_fmamk_f32 v151, v151, 0x3c800000, v36
	v_fmamk_f32 v153, v153, 0x3c800000, v36
	v_fmamk_f32 v155, v155, 0x3c800000, v36
	v_fmamk_f32 v157, v157, 0x3c800000, v36
	v_fmamk_f32 v159, v159, 0x3c800000, v36
	v_cmp_gt_f32_e32 vcc, s58, v151
	v_mul_f32_e32 v150, 0x4b800000, v151
	s_nop 0
	v_cndmask_b32_e32 v151, v151, v150, vcc
	v_rsq_f32_e32 v151, v151
	s_nop 0
	v_mul_f32_e32 v150, 0x45800000, v151
	v_cndmask_b32_e32 v151, v151, v150, vcc
	v_cmp_gt_f32_e32 vcc, s58, v153
	v_mul_f32_e32 v152, 0x4b800000, v153
	s_nop 0
	v_cndmask_b32_e32 v153, v153, v152, vcc
	v_rsq_f32_e32 v153, v153
	s_nop 0
	v_mul_f32_e32 v152, 0x45800000, v153
	v_cndmask_b32_e32 v153, v153, v152, vcc
	v_cmp_gt_f32_e32 vcc, s58, v155
	v_mul_f32_e32 v154, 0x4b800000, v155
	s_nop 0
	v_cndmask_b32_e32 v155, v155, v154, vcc
	v_rsq_f32_e32 v155, v155
	s_nop 0
	v_mul_f32_e32 v154, 0x45800000, v155
	v_cndmask_b32_e32 v155, v155, v154, vcc
	v_cmp_gt_f32_e32 vcc, s58, v157
	v_mul_f32_e32 v156, 0x4b800000, v157
	s_nop 0
	v_cndmask_b32_e32 v157, v157, v156, vcc
	v_rsq_f32_e32 v157, v157
	s_nop 0
	v_mul_f32_e32 v156, 0x45800000, v157
	v_cndmask_b32_e32 v157, v157, v156, vcc
	v_cmp_gt_f32_e32 vcc, s58, v159
	v_mul_f32_e32 v158, 0x4b800000, v159
	s_nop 0
	v_cndmask_b32_e32 v159, v159, v158, vcc
	v_rsq_f32_e32 v159, v159
	s_nop 0
	v_mul_f32_e32 v158, 0x45800000, v159
	v_cndmask_b32_e32 v159, v159, v158, vcc
	v_mul_f32_e32 v151, v151, v23
	v_mul_f32_e32 v151, v6, v151
	v_mul_f32_e32 v153, v153, v22
	v_mul_f32_e32 v153, v3, v153
	v_mul_f32_e32 v155, v155, v21
	v_mul_f32_e32 v155, v6, v155
	v_mul_f32_e32 v157, v157, v20
	v_mul_f32_e32 v157, v3, v157
	v_mul_f32_e32 v159, v159, v19
	v_mul_f32_e32 v159, v6, v159
	s_andn2_b64 vcc, exec, s[12:13]
	s_cbranch_vccnz .Lmy_norope_2
	ds_bpermute_b32 v150, v8, v151
	ds_bpermute_b32 v152, v8, v153
	ds_bpermute_b32 v154, v8, v155
	ds_bpermute_b32 v156, v8, v157
	ds_bpermute_b32 v158, v8, v159
	s_waitcnt lgkmcnt(0)
	v_mul_f32_e32 v150, v16, v150
	v_cndmask_b32_e64 v150, v150, -v150, s[2:3]
	v_fmac_f32_e32 v150, v15, v151
	v_mov_b32_e32 v151, v150
	v_mul_f32_e32 v152, v16, v152
	v_cndmask_b32_e64 v152, v152, -v152, s[2:3]
	v_fmac_f32_e32 v152, v15, v153
	v_mov_b32_e32 v153, v152
	v_mul_f32_e32 v154, v16, v154
	v_cndmask_b32_e64 v154, v154, -v154, s[2:3]
	v_fmac_f32_e32 v154, v15, v155
	v_mov_b32_e32 v155, v154
	v_mul_f32_e32 v156, v16, v156
	v_cndmask_b32_e64 v156, v156, -v156, s[2:3]
	v_fmac_f32_e32 v156, v15, v157
	v_mov_b32_e32 v157, v156
	v_mul_f32_e32 v158, v16, v158
	v_cndmask_b32_e64 v158, v158, -v158, s[2:3]
	v_fmac_f32_e32 v158, v15, v159
	v_mov_b32_e32 v159, v158
; DEVI bf16_t f2bf(float f) { return (bf16_t)(pk2(f, 0.f) & 0xffffu); }
; DEVI void prep1_qk(int sw, const P& p, int item) {
;     ...
;   for (int hm = 0; hm < 16; ++hm) {
;     float ss = wave_sum(a[hm] * a[hm]);
;     float rs = rsqrtf(ss * (1.f / 64.f) + EPS);
;     float x = a[hm] * rs * ((hm & 1) ? g1 : g0);
;     if (pp >= CTX) x = rope64(x, lane, pp - CTX);
;     if (which == 0) x *= 0.125f * LOG2E;
;     q[hm * 64 + lane] = f2bf(x);
.Lmy_norope_2:
	v_mul_f32_e32 v150, 0x3e38aa3b, v151
	v_cndmask_b32_e64 v151, v151, v150, s[0:1]
	v_cvt_pk_bf16_f32 v151, v151, s0
	global_store_short v[0:1], v151, off offset:768
	v_mul_f32_e32 v152, 0x3e38aa3b, v153
	v_cndmask_b32_e64 v153, v153, v152, s[0:1]
	v_cvt_pk_bf16_f32 v153, v153, s0
	global_store_short v[0:1], v153, off offset:896
	v_mul_f32_e32 v154, 0x3e38aa3b, v155
	v_cndmask_b32_e64 v155, v155, v154, s[0:1]
	v_cvt_pk_bf16_f32 v155, v155, s0
	global_store_short v[0:1], v155, off offset:1024
	v_mul_f32_e32 v156, 0x3e38aa3b, v157
	v_cndmask_b32_e64 v157, v157, v156, s[0:1]
	v_cvt_pk_bf16_f32 v157, v157, s0
	global_store_short v[0:1], v157, off offset:1152
	v_mul_f32_e32 v158, 0x3e38aa3b, v159
	v_cndmask_b32_e64 v159, v159, v158, s[0:1]
	v_cvt_pk_bf16_f32 v159, v159, s0
	global_store_short v[0:1], v159, off offset:1280
	v_lshlrev_b32_e32 v18, 16, v18
	v_lshlrev_b32_e32 v17, 16, v17
	v_lshlrev_b32_e32 v14, 16, v14
	v_lshlrev_b32_e32 v7, 16, v7
	v_lshlrev_b32_e32 v4, 16, v4
	v_mul_f32_e32 v150, v18, v18
	v_mul_f32_e32 v152, v17, v17
	v_mul_f32_e32 v154, v14, v14
	v_mul_f32_e32 v156, v7, v7
	v_mul_f32_e32 v158, v4, v4
	ds_bpermute_b32 v151, v9, v150
	ds_bpermute_b32 v153, v9, v152
	ds_bpermute_b32 v155, v9, v154
	ds_bpermute_b32 v157, v9, v156
	ds_bpermute_b32 v159, v9, v158
	s_waitcnt lgkmcnt(0)
	v_fmac_f32_e32 v151, v18, v18
	v_fmac_f32_e32 v153, v17, v17
	v_fmac_f32_e32 v155, v14, v14
	v_fmac_f32_e32 v157, v7, v7
	v_fmac_f32_e32 v159, v4, v4
	ds_bpermute_b32 v150, v8, v151
	ds_bpermute_b32 v152, v8, v153
	ds_bpermute_b32 v154, v8, v155
	ds_bpermute_b32 v156, v8, v157
	ds_bpermute_b32 v158, v8, v159
	s_waitcnt lgkmcnt(0)
	v_add_f32_e32 v151, v151, v150
	v_add_f32_e32 v153, v153, v152
	v_add_f32_e32 v155, v155, v154
	v_add_f32_e32 v157, v157, v156
	v_add_f32_e32 v159, v159, v158
	ds_bpermute_b32 v150, v10, v151
	ds_bpermute_b32 v152, v10, v153
	ds_bpermute_b32 v154, v10, v155
	ds_bpermute_b32 v156, v10, v157
	ds_bpermute_b32 v158, v10, v159
	s_waitcnt lgkmcnt(0)
	v_add_f32_e32 v151, v151, v150
	v_add_f32_e32 v153, v153, v152
	v_add_f32_e32 v155, v155, v154
	v_add_f32_e32 v157, v157, v156
	v_add_f32_e32 v159, v159, v158
	ds_bpermute_b32 v150, v11, v151
	ds_bpermute_b32 v152, v11, v153
	ds_bpermute_b32 v154, v11, v155
	ds_bpermute_b32 v156, v11, v157
	ds_bpermute_b32 v158, v11, v159
	s_waitcnt lgkmcnt(0)
	v_add_f32_e32 v151, v151, v150
	v_add_f32_e32 v153, v153, v152
	v_add_f32_e32 v155, v155, v154
	v_add_f32_e32 v157, v157, v156
	v_add_f32_e32 v159, v159, v158
	ds_bpermute_b32 v150, v12, v151
	ds_bpermute_b32 v152, v12, v153
	ds_bpermute_b32 v154, v12, v155
	ds_bpermute_b32 v156, v12, v157
	ds_bpermute_b32 v158, v12, v159
	s_waitcnt lgkmcnt(0)
	v_add_f32_e32 v151, v151, v150
	v_add_f32_e32 v153, v153, v152
	v_add_f32_e32 v155, v155, v154
	v_add_f32_e32 v157, v157, v156
	v_add_f32_e32 v159, v159, v158
	ds_bpermute_b32 v150, v13, v151
	ds_bpermute_b32 v152, v13, v153
	ds_bpermute_b32 v154, v13, v155
	ds_bpermute_b32 v156, v13, v157
	ds_bpermute_b32 v158, v13, v159
	s_waitcnt lgkmcnt(0)
	v_add_f32_e32 v151, v151, v150
	v_add_f32_e32 v153, v153, v152
	v_add_f32_e32 v155, v155, v154
	v_add_f32_e32 v157, v157, v156
	v_add_f32_e32 v159, v159, v158
	v_fmamk_f32 v151, v151, 0x3c800000, v36
	v_fmamk_f32 v153, v153, 0x3c800000, v36
	v_fmamk_f32 v155, v155, 0x3c800000, v36
	v_fmamk_f32 v157, v157, 0x3c800000, v36
	v_fmamk_f32 v159, v159, 0x3c800000, v36
	v_cmp_gt_f32_e32 vcc, s58, v151
	v_mul_f32_e32 v150, 0x4b800000, v151
	s_nop 0
	v_cndmask_b32_e32 v151, v151, v150, vcc
	v_rsq_f32_e32 v151, v151
	s_nop 0
	v_mul_f32_e32 v150, 0x45800000, v151
	v_cndmask_b32_e32 v151, v151, v150, vcc
	v_cmp_gt_f32_e32 vcc, s58, v153
	v_mul_f32_e32 v152, 0x4b800000, v153
	s_nop 0
	v_cndmask_b32_e32 v153, v153, v152, vcc
	v_rsq_f32_e32 v153, v153
	s_nop 0
	v_mul_f32_e32 v152, 0x45800000, v153
	v_cndmask_b32_e32 v153, v153, v152, vcc
	v_cmp_gt_f32_e32 vcc, s58, v155
	v_mul_f32_e32 v154, 0x4b800000, v155
	s_nop 0
	v_cndmask_b32_e32 v155, v155, v154, vcc
	v_rsq_f32_e32 v155, v155
	s_nop 0
	v_mul_f32_e32 v154, 0x45800000, v155
	v_cndmask_b32_e32 v155, v155, v154, vcc
	v_cmp_gt_f32_e32 vcc, s58, v157
	v_mul_f32_e32 v156, 0x4b800000, v157
	s_nop 0
	v_cndmask_b32_e32 v157, v157, v156, vcc
	v_rsq_f32_e32 v157, v157
	s_nop 0
	v_mul_f32_e32 v156, 0x45800000, v157
	v_cndmask_b32_e32 v157, v157, v156, vcc
	v_cmp_gt_f32_e32 vcc, s58, v159
	v_mul_f32_e32 v158, 0x4b800000, v159
	s_nop 0
	v_cndmask_b32_e32 v159, v159, v158, vcc
	v_rsq_f32_e32 v159, v159
	s_nop 0
	v_mul_f32_e32 v158, 0x45800000, v159
	v_cndmask_b32_e32 v159, v159, v158, vcc
	v_mul_f32_e32 v151, v151, v18
	v_mul_f32_e32 v151, v3, v151
	v_mul_f32_e32 v153, v153, v17
	v_mul_f32_e32 v153, v6, v153
	v_mul_f32_e32 v155, v155, v14
	v_mul_f32_e32 v155, v3, v155
	v_mul_f32_e32 v157, v157, v7
	v_mul_f32_e32 v157, v6, v157
	v_mul_f32_e32 v159, v159, v4
	v_mul_f32_e32 v159, v3, v159
	s_andn2_b64 vcc, exec, s[12:13]
	s_cbranch_vccnz .Lmy_norope_3
	ds_bpermute_b32 v150, v8, v151
	ds_bpermute_b32 v152, v8, v153
	ds_bpermute_b32 v154, v8, v155
	ds_bpermute_b32 v156, v8, v157
	ds_bpermute_b32 v158, v8, v159
	s_waitcnt lgkmcnt(0)
	v_mul_f32_e32 v150, v16, v150
	v_cndmask_b32_e64 v150, v150, -v150, s[2:3]
	v_fmac_f32_e32 v150, v15, v151
	v_mov_b32_e32 v151, v150
	v_mul_f32_e32 v152, v16, v152
	v_cndmask_b32_e64 v152, v152, -v152, s[2:3]
	v_fmac_f32_e32 v152, v15, v153
	v_mov_b32_e32 v153, v152
	v_mul_f32_e32 v154, v16, v154
	v_cndmask_b32_e64 v154, v154, -v154, s[2:3]
	v_fmac_f32_e32 v154, v15, v155
	v_mov_b32_e32 v155, v154
	v_mul_f32_e32 v156, v16, v156
	v_cndmask_b32_e64 v156, v156, -v156, s[2:3]
	v_fmac_f32_e32 v156, v15, v157
	v_mov_b32_e32 v157, v156
	v_mul_f32_e32 v158, v16, v158
	v_cndmask_b32_e64 v158, v158, -v158, s[2:3]
	v_fmac_f32_e32 v158, v15, v159
	v_mov_b32_e32 v159, v158
.Lmy_norope_3:
	v_mul_f32_e32 v150, 0x3e38aa3b, v151
	v_cndmask_b32_e64 v151, v151, v150, s[0:1]
	v_cvt_pk_bf16_f32 v151, v151, s0
	global_store_short v[0:1], v151, off offset:1408
	v_mul_f32_e32 v152, 0x3e38aa3b, v153
	v_cndmask_b32_e64 v153, v153, v152, s[0:1]
	v_cvt_pk_bf16_f32 v153, v153, s0
	global_store_short v[0:1], v153, off offset:1536
	v_mul_f32_e32 v154, 0x3e38aa3b, v155
	v_cndmask_b32_e64 v155, v155, v154, s[0:1]
	v_cvt_pk_bf16_f32 v155, v155, s0
	global_store_short v[0:1], v155, off offset:1664
	v_mul_f32_e32 v156, 0x3e38aa3b, v157
	v_cndmask_b32_e64 v157, v157, v156, s[0:1]
	v_cvt_pk_bf16_f32 v157, v157, s0
	global_store_short v[0:1], v157, off offset:1792
	v_mul_f32_e32 v158, 0x3e38aa3b, v159
	v_cndmask_b32_e64 v159, v159, v158, s[0:1]
	v_cvt_pk_bf16_f32 v159, v159, s0
	global_store_short v[0:1], v159, off offset:1920
	s_not_b64 s[4:5], s[12:13]
	s_mov_b64 s[2:3], 0
